# mLSTM staging: Q and K chunk loads use a coalesced lane mapping (8 tokens x 8 chunks per wave, 16 cache lines per load instead of 64); LDS images unchanged, per-token scale fetched with ds_bpermute
# speedup vs baseline: 1.0249x; 1.0184x over previous
.LBB0_639:
	s_or_b64 exec, exec, s[2:3]
	s_ashr_i32 s0, s48, 4
	s_bfe_u32 s4, s48, 0x20002
	s_lshl_b32 s26, s0, 2
	s_or_b32 s2, s26, s4
	s_waitcnt vmcnt(10)
	v_and_b32_e32 v46, 63, v69
	s_lshl_b32 s49, s0, 11
	s_ashr_i32 s3, s2, 31
	v_or_b32_e32 v22, s49, v46
	s_lshl_b64 s[2:3], s[2:3], 15
	v_readlane_b32 s8, v245, 49
	v_ashrrev_i32_e32 v23, 31, v22
	v_lshl_or_b32 v0, v46, 4, s2
	v_mov_b32_e32 v1, s3
	v_readlane_b32 s12, v245, 53
	v_readlane_b32 s13, v245, 54
	v_readlane_b32 s9, v245, 50
	s_lshl_b32 s0, s4, 8
	s_waitcnt vmcnt(4)
	v_lshl_add_u64 v[28:29], s[12:13], 0, v[0:1]
	v_lshlrev_b64 v[0:1], 11, v[22:23]
	v_lshl_add_u64 v[0:1], s[8:9], 0, v[0:1]
	v_mad_i64_i32 v[26:27], s[2:3], v22, s37, v[38:39]
	v_ashrrev_i32_e32 v5, 6, v69
	v_lshl_add_u64 v[0:1], v[0:1], 0, s[0:1]
	v_lshl_add_u64 v[26:27], v[26:27], 0, s[0:1]
	s_lshl_b32 s0, s48, 5
	v_lshlrev_b32_e32 v24, 4, v5
	s_and_b32 s0, s0, 0x60
	v_ashrrev_i32_e32 v25, 31, v24
	s_lshl_b32 s0, s0, 1
	v_lshl_add_u64 v[6:7], v[24:25], 1, v[0:1]
	s_waitcnt vmcnt(0)
	v_lshl_add_u64 v[30:31], v[26:27], 0, s[0:1]
	v_lshlrev_b32_e32 v26, 2, v5
	v_lshrrev_b32_e32 v137, 3, v46
	v_lshl_add_u32 v137, v5, 3, v137
	v_sub_u32_e32 v137, v137, v46
	v_and_b32_e32 v138, 7, v46
	v_sub_u32_e32 v138, v138, v5
	v_lshlrev_b32_e32 v138, 5, v138
	v_lshl_add_u32 v134, v137, 11, v138
	v_ashrrev_i32_e32 v135, 31, v134
	v_mul_i32_i24_e32 v139, 0x110, v137
	v_add_u32_e32 v139, v139, v138
	v_and_b32_e32 v144, 7, v46
	v_lshrrev_b32_e32 v145, 3, v46
	v_lshl_add_u32 v145, v5, 3, v145
	v_lshlrev_b32_e32 v146, 1, v144
	v_and_b32_e32 v147, 7, v146
	v_lshlrev_b32_e32 v147, 3, v147
	v_xor_b32_e32 v147, v145, v147
	v_mul_u32_u24_e32 v148, 0x900, v144
	v_lshl_add_u32 v140, v147, 1, v148
	v_add_u32_e32 v146, 1, v146
	v_and_b32_e32 v146, 7, v146
	v_lshlrev_b32_e32 v146, 3, v146
	v_xor_b32_e32 v146, v145, v146
	v_lshl_add_u32 v141, v146, 1, v148
	v_lshlrev_b32_e32 v143, 2, v145
	v_lshl_add_u64 v[132:133], v[6:7], 0, v[134:135]
	global_load_dwordx4 v[10:13], v[28:29], off
	global_load_dwordx4 v[14:17], v[132:133], off offset:16
	global_load_dwordx4 v[18:21], v[132:133], off
	global_load_dwordx4 v[0:3], v[132:133], off offset:1040
	s_nop 0
	global_load_dwordx4 v[6:9], v[132:133], off offset:1024
	v_ashrrev_i32_e32 v27, 31, v26
	v_lshl_add_u64 v[30:31], v[26:27], 1, v[30:31]
	global_load_dwordx2 v[30:31], v[30:31], off offset:2048
	s_lshl_b32 s4, s4, 7
	v_cmp_gt_u32_e64 s[8:9], 64, v69
	v_readlane_b32 s10, v245, 51
	v_readlane_b32 s11, v245, 52
	v_readlane_b32 s14, v245, 55
	v_readlane_b32 s15, v245, 56
	s_waitcnt vmcnt(5)
	v_readlane_b32 s5, v10, 63
	v_readlane_b32 s6, v12, 63
	s_and_saveexec_b64 s[2:3], s[8:9]
	s_cbranch_execz .LBB0_641
	v_add_f32_e32 v23, 0, v10
	v_add_f32_e32 v12, v10, v12
	v_max_f32_e32 v12, v23, v12
	v_sub_f32_e32 v23, v23, v12
	v_mul_f32_e32 v23, 0x3fb8aa3b, v23
	v_mul_f32_e32 v32, 0xbfb8aa3b, v12
	v_exp_f32_e32 v23, v23
	v_exp_f32_e32 v32, v32
	v_lshl_add_u32 v13, v46, 2, s38
	v_sub_f32_e32 v10, v10, v12
	v_lshl_add_u32 v4, v69, 2, s38
	ds_write_b32 v13, v10
	ds_write2st64_b32 v4, v11, v23 offset0:1 offset1:2
	ds_write_b32 v4, v32 offset:768
.LBB0_641:
	s_or_b64 exec, exec, s[2:3]
	v_mov_b32_e32 v4, s6
	v_add_f32_e32 v10, s5, v4
	v_add_f32_e64 v12, s5, 0
	v_max_f32_e32 v75, v12, v10
	v_sub_f32_e32 v10, v12, v75
	v_mul_f32_e32 v10, 0x3fb8aa3b, v10
	v_exp_f32_e32 v54, v10
	v_add_f32_e32 v10, s5, v11
	v_sub_f32_e32 v10, v10, v75
	v_mul_f32_e32 v10, 0x3fb8aa3b, v10
	v_exp_f32_e32 v10, v10
	s_nop 0
	ds_bpermute_b32 v142, v143, v10
	v_mul_u32_u24_e32 v11, 0x88, v46
	v_lshlrev_b32_e32 v11, 1, v11
	v_lshlrev_b32_e32 v34, 1, v24
	v_add3_u32 v76, 0, v11, v34
	v_add_u32_e32 v136, v76, v139
	s_waitcnt vmcnt(3)
	ds_write_b128 v136, v[18:21]
	ds_write_b128 v136, v[14:17] offset:16
	s_waitcnt vmcnt(1)
	ds_write_b128 v136, v[6:9] offset:17408
	ds_write_b128 v136, v[0:3] offset:17424
	v_lshlrev_b32_e32 v12, 16, v6
	v_mul_lo_u32 v13, v5, s39
	v_and_b32_e32 v6, 0xffff0000, v6
	v_bitop3_b32 v11, v24, v46, 48 bitop3:0x6c
	v_add_u32_e32 v13, 0, v13
	s_waitcnt lgkmcnt(0)
	v_mul_f32_e32 v6, v142, v6
	v_lshl_add_u32 v73, v11, 1, v13
	v_cvt_pk_bf16_f32 v6, v6, s0
	ds_write_b16 v140, v6 offset:34960
	v_lshlrev_b32_e32 v6, 16, v7
	v_mul_f32_e32 v6, v142, v6
	v_cvt_pk_bf16_f32 v6, v6, s0
	ds_write_b16 v140, v6 offset:35104
	v_and_b32_e32 v6, 0xffff0000, v7
	v_mul_f32_e32 v6, v142, v6
	v_cvt_pk_bf16_f32 v6, v6, s0
	ds_write_b16 v140, v6 offset:35248
	v_lshlrev_b32_e32 v6, 16, v8
	v_mul_f32_e32 v6, v142, v6
	v_cvt_pk_bf16_f32 v6, v6, s0
	ds_write_b16 v140, v6 offset:35392
	v_and_b32_e32 v6, 0xffff0000, v8
	v_mul_f32_e32 v6, v142, v6
	v_cvt_pk_bf16_f32 v6, v6, s0
	ds_write_b16 v140, v6 offset:35536
	v_lshlrev_b32_e32 v6, 16, v9
	v_mul_f32_e32 v6, v142, v6
	v_cvt_pk_bf16_f32 v6, v6, s0
	ds_write_b16 v140, v6 offset:35680
	v_and_b32_e32 v6, 0xffff0000, v9
	v_mul_f32_e32 v6, v142, v6
	v_and_b32_e32 v35, 48, v24
	v_cvt_pk_bf16_f32 v6, v6, s0
	v_lshlrev_b32_e32 v7, 16, v0
	v_and_b32_e32 v0, 0xffff0000, v0
	ds_write_b16 v140, v6 offset:35824
	v_bitop3_b32 v6, v35, v46, 8 bitop3:0x36
	v_mul_f32_e32 v0, v142, v0
	v_lshl_add_u32 v74, v6, 1, v13
	v_cvt_pk_bf16_f32 v0, v0, s0
	ds_write_b16 v141, v0 offset:36112
	v_lshlrev_b32_e32 v0, 16, v1
	v_mul_f32_e32 v0, v142, v0
	v_cvt_pk_bf16_f32 v0, v0, s0
	ds_write_b16 v141, v0 offset:36256
	v_and_b32_e32 v0, 0xffff0000, v1
	v_mul_f32_e32 v0, v142, v0
	v_cvt_pk_bf16_f32 v0, v0, s0
	ds_write_b16 v141, v0 offset:36400
	v_lshlrev_b32_e32 v0, 16, v2
	v_mul_f32_e32 v0, v142, v0
	v_cvt_pk_bf16_f32 v0, v0, s0
	ds_write_b16 v141, v0 offset:36544
	v_and_b32_e32 v0, 0xffff0000, v2
	v_mul_f32_e32 v0, v142, v0
	v_cvt_pk_bf16_f32 v0, v0, s0
	ds_write_b16 v141, v0 offset:36688
	v_lshlrev_b32_e32 v0, 16, v3
	v_mul_f32_e32 v0, v142, v0
	v_cvt_pk_bf16_f32 v0, v0, s0
	ds_write_b16 v141, v0 offset:36832
	v_and_b32_e32 v0, 0xffff0000, v3
	v_mul_f32_e32 v7, v142, v7
	v_mul_f32_e32 v0, v142, v0
	s_lshr_b32 s2, s48, 2
	v_cvt_pk_bf16_f32 v7, v7, s0
	v_cvt_pk_bf16_f32 v0, v0, s0
	v_or_b32_e32 v6, 64, v22
	s_and_b32 s27, s2, 3
	v_mul_f32_e32 v12, v142, v12
	ds_write_b16 v141, v7 offset:35968
	ds_write_b16 v141, v0 offset:36976
	v_mad_u64_u32 v[0:1], s[2:3], v5, s42, v[46:47]
	v_ashrrev_i32_e32 v7, 31, v6
	v_readlane_b32 s56, v245, 49
	v_cvt_pk_bf16_f32 v12, v12, s0
	v_lshl_add_u32 v77, v0, 1, 0
	v_lshlrev_b64 v[0:1], 11, v[6:7]
	v_readlane_b32 s57, v245, 50
	ds_write_b16 v140, v12 offset:34816
	s_waitcnt vmcnt(0)
	ds_write_b16 v77, v30 offset:53248
	ds_write_b16_d16_hi v77, v30 offset:53392
	ds_write_b16 v77, v31 offset:53536
	ds_write_b16_d16_hi v77, v31 offset:53680
	v_lshl_add_u64 v[0:1], s[56:57], 0, v[0:1]
	s_lshl_b32 s24, s4, 1
	s_mov_b32 s25, s1
	global_load_dwordx4 v[12:15], v[28:29], off offset:1024
	v_lshl_add_u64 v[0:1], v[0:1], 0, s[24:25]
	v_lshlrev_b64 v[28:29], 1, v[24:25]
	v_mad_i64_i32 v[6:7], s[2:3], v6, s37, v[38:39]
	v_lshl_add_u64 v[8:9], v[0:1], 0, v[28:29]
	v_lshl_add_u64 v[132:133], v[8:9], 0, v[134:135]
	v_lshl_add_u64 v[6:7], v[6:7], 0, s[24:25]
	global_load_dwordx4 v[16:19], v[132:133], off offset:16
	global_load_dwordx4 v[20:23], v[132:133], off
	global_load_dwordx4 v[0:3], v[132:133], off offset:1040
	s_nop 0
	global_load_dwordx4 v[8:11], v[132:133], off offset:1024
	v_lshl_add_u64 v[6:7], v[6:7], 0, s[0:1]
	v_lshlrev_b64 v[26:27], 1, v[26:27]
	v_lshl_add_u64 v[6:7], v[6:7], 0, v[26:27]
	global_load_dwordx2 v[48:49], v[6:7], off offset:2048
	v_and_b32_e32 v33, 15, v69
	v_lshrrev_b32_e32 v30, 1, v69
	v_mul_u32_u24_e32 v25, 0x88, v33
	v_and_b32_e32 v30, 24, v30
	v_bfe_u32 v6, v69, 6, 1
	v_lshlrev_b32_e32 v25, 1, v25
	v_lshlrev_b32_e32 v80, 1, v30
	v_lshrrev_b32_e32 v32, 4, v46
	v_ashrrev_i32_e32 v5, 7, v69
	v_lshlrev_b32_e32 v7, 1, v6
	v_add3_u32 v56, 0, v25, v80
	v_mad_u32_u24 v30, v6, s43, v43
	v_or_b32_e32 v24, v24, v33
	v_mul_u32_u24_e32 v36, 0x48, v33
	s_add_u32 s25, s82, s24
	v_mad_u64_u32 v[44:45], s[2:3], v5, s43, v[56:57]
	v_lshlrev_b32_e32 v42, 4, v6
	v_add3_u32 v68, v30, v25, v80
	v_add3_u32 v57, s44, v25, v80
	v_and_b32_e32 v25, 8, v69
	v_lshlrev_b32_e32 v52, 3, v32
	v_mul_lo_u32 v24, v24, s45
	v_mul_u32_u24_e32 v79, 0x900, v6
	v_lshlrev_b32_e32 v81, 1, v36
	v_mul_u32_u24_e32 v88, 0x2200, v6
	v_lshlrev_b32_e32 v36, 5, v6
	v_or_b32_e32 v6, 1, v7
	s_addc_u32 s51, s83, 0
	v_or_b32_e32 v30, v35, v25
	v_add_u32_e32 v24, 0, v24
	v_mul_u32_u24_e32 v83, 0x1100, v6
	v_lshl_or_b32 v72, v6, 4, v33
	v_bitop3_b32 v6, v35, v52, v25 bitop3:0x36
	s_add_u32 s52, s25, s0
	v_lshl_add_u32 v71, v6, 1, v24
	v_bitop3_b32 v6, v52, v30, 32 bitop3:0x36
	s_addc_u32 s53, s51, 0
	v_cmp_le_i32_e64 s[20:21], v7, v5
	v_cmp_lt_i32_e64 s[10:11], v7, v5
	v_lshl_add_u32 v70, v6, 1, v24
	v_lshl_add_u64 v[6:7], s[52:53], 0, v[36:37]
	s_add_u32 s52, s56, s24
	s_addc_u32 s53, s57, 0
	s_add_u32 s25, s80, s24
	s_addc_u32 s51, s81, 0
	v_lshl_add_u64 v[58:59], s[52:53], 0, v[28:29]
	s_add_u32 s52, s25, s0
	s_addc_u32 s53, s51, 0
	s_add_i32 s26, s26, s27
	v_mul_lo_u32 v31, v5, s39
	s_ashr_i32 s27, s26, 31
	s_waitcnt vmcnt(5)
	v_lshlrev_b32_e32 v15, 4, v5
	v_lshlrev_b32_e32 v40, 2, v32
	v_add_u32_e32 v31, s46, v31
	s_lshl_b64 s[26:27], s[26:27], 15
	v_or_b32_e32 v86, v40, v15
	v_add3_u32 v55, v31, v81, v80
	v_lshlrev_b32_e32 v31, 1, v33
	v_or_b32_e32 v78, v36, v33
	s_add_u32 s26, s28, s26
	v_mov_b32_e32 v4, 0
	v_add3_u32 v31, s35, v34, v31
	v_lshl_add_u32 v34, v78, 1, s46
	v_mul_lo_u32 v45, v86, s45
	v_or_b32_e32 v87, 1, v86
	v_or_b32_e32 v85, 2, v86
	v_or_b32_e32 v84, 3, v86
	v_lshl_add_u32 v5, v72, 1, s46
	v_mul_u32_u24_e32 v24, 0x440, v32
	v_mov_b32_e32 v53, v37
	v_lshlrev_b32_e32 v36, 4, v46
	s_addc_u32 s27, s29, s27
	s_add_i32 s25, s49, 0x80
	s_mov_b32 s50, 1
	v_or_b32_e32 v47, v15, v33
	v_cmp_le_i32_e64 s[18:19], v78, v86
	v_cmp_le_i32_e64 s[16:17], v78, v87
	v_cmp_le_i32_e64 s[14:15], v78, v85
	v_cmp_le_i32_e64 s[12:13], v78, v84
	v_cmp_le_i32_e64 s[6:7], v72, v86
	v_cmp_le_i32_e64 s[4:5], v72, v87
	v_cmp_le_i32_e64 s[2:3], v72, v85
	v_cmp_le_i32_e32 vcc, v72, v84
	v_mul_u32_u24_e32 v82, 0x90, v33
	v_lshl_add_u64 v[50:51], v[6:7], 0, v[52:53]
	v_lshl_add_u64 v[60:61], s[52:53], 0, v[26:27]
	v_lshl_add_u64 v[62:63], s[26:27], 0, v[36:37]
	v_add_u32_e32 v64, s25, v46
	v_add3_u32 v66, s49, v15, v33
	v_add_u32_e32 v53, v34, v45
	v_add_u32_e32 v36, v5, v45
	v_add_u32_e32 v45, v31, v24
	v_mov_b32_e32 v5, v4
	v_mov_b32_e32 v6, v4
	v_mov_b32_e32 v7, v4
	v_mov_b32_e32 v28, v4
	v_mov_b32_e32 v29, v4
	v_mov_b32_e32 v30, v4
	v_mov_b32_e32 v31, v4
	v_mov_b32_e32 v24, v4
	v_mov_b32_e32 v25, v4
	v_mov_b32_e32 v26, v4
	v_mov_b32_e32 v27, v4
	v_readlane_b32 s58, v245, 51
	v_readlane_b32 s59, v245, 52
	v_readlane_b32 s60, v245, 53
	v_readlane_b32 s61, v245, 54
	v_readlane_b32 s62, v245, 55
	v_readlane_b32 s63, v245, 56
	s_branch .LBB0_643
.LBB0_642:
	s_or_b64 exec, exec, s[26:27]
	v_mov_b32_e32 v12, s52
	v_add_f32_e32 v12, s51, v12
	v_add_f32_e32 v34, s51, v75
	v_max_f32_e32 v75, v34, v12
	v_add_f32_e32 v12, s51, v13
	v_sub_f32_e32 v12, v12, v75
	v_mul_f32_e32 v12, 0x3fb8aa3b, v12
	v_exp_f32_e32 v12, v12
	s_nop 0
	ds_bpermute_b32 v142, v143, v12
	s_waitcnt vmcnt(4)
	ds_write_b128 v136, v[20:23]
	ds_write_b128 v136, v[16:19] offset:16
	s_waitcnt vmcnt(2)
	ds_write_b128 v136, v[8:11] offset:17408
	ds_write_b128 v136, v[0:3] offset:17424
	v_lshlrev_b32_e32 v13, 16, v8
	v_and_b32_e32 v8, 0xffff0000, v8
	s_waitcnt lgkmcnt(0)
	v_mul_f32_e32 v8, v142, v8
	v_cvt_pk_bf16_f32 v8, v8, s0
	ds_write_b16 v140, v8 offset:34960
	v_lshlrev_b32_e32 v8, 16, v9
	v_mul_f32_e32 v8, v142, v8
	v_cvt_pk_bf16_f32 v8, v8, s0
	ds_write_b16 v140, v8 offset:35104
	v_and_b32_e32 v8, 0xffff0000, v9
	v_mul_f32_e32 v8, v142, v8
	v_cvt_pk_bf16_f32 v8, v8, s0
	ds_write_b16 v140, v8 offset:35248
	v_lshlrev_b32_e32 v8, 16, v10
	v_mul_f32_e32 v8, v142, v8
	v_cvt_pk_bf16_f32 v8, v8, s0
	ds_write_b16 v140, v8 offset:35392
	v_and_b32_e32 v8, 0xffff0000, v10
	v_mul_f32_e32 v8, v142, v8
	v_cvt_pk_bf16_f32 v8, v8, s0
	ds_write_b16 v140, v8 offset:35536
	v_lshlrev_b32_e32 v8, 16, v11
	v_mul_f32_e32 v8, v142, v8
	v_cvt_pk_bf16_f32 v8, v8, s0
	ds_write_b16 v140, v8 offset:35680
	v_and_b32_e32 v8, 0xffff0000, v11
	v_mul_f32_e32 v8, v142, v8
	v_cvt_pk_bf16_f32 v8, v8, s0
	ds_write_b16 v140, v8 offset:35824
	v_lshlrev_b32_e32 v8, 16, v0
	v_and_b32_e32 v0, 0xffff0000, v0
	v_mul_f32_e32 v0, v142, v0
	v_cvt_pk_bf16_f32 v0, v0, s0
	ds_write_b16 v141, v0 offset:36112
	v_lshlrev_b32_e32 v0, 16, v1
	v_mul_f32_e32 v0, v142, v0
	v_cvt_pk_bf16_f32 v0, v0, s0
	ds_write_b16 v141, v0 offset:36256
	v_and_b32_e32 v0, 0xffff0000, v1
	v_mul_f32_e32 v0, v142, v0
	v_cvt_pk_bf16_f32 v0, v0, s0
	ds_write_b16 v141, v0 offset:36400
	v_lshlrev_b32_e32 v0, 16, v2
	v_mul_f32_e32 v0, v142, v0
	v_cvt_pk_bf16_f32 v0, v0, s0
	ds_write_b16 v141, v0 offset:36544
	v_and_b32_e32 v0, 0xffff0000, v2
	v_mul_f32_e32 v0, v142, v0
	v_cvt_pk_bf16_f32 v0, v0, s0
	ds_write_b16 v141, v0 offset:36688
	v_lshlrev_b32_e32 v0, 16, v3
	v_mul_f32_e32 v0, v142, v0
	v_cvt_pk_bf16_f32 v0, v0, s0
	ds_write_b16 v141, v0 offset:36832
	v_and_b32_e32 v0, 0xffff0000, v3
	v_mul_f32_e32 v0, v142, v0
	s_mulk_i32 s25, 0x1b00
	v_mul_f32_e32 v13, v142, v13
	v_mul_f32_e32 v8, v142, v8
	v_cvt_pk_bf16_f32 v0, v0, s0
	v_cvt_pk_bf16_f32 v13, v13, s0
	v_cvt_pk_bf16_f32 v8, v8, s0
	ds_write_b16 v141, v0 offset:36976
	v_add_u32_e32 v0, s25, v77
	v_ashrrev_i32_e32 v65, 31, v64
	ds_write_b16 v140, v13 offset:34816
	ds_write_b16 v141, v8 offset:35968
	s_waitcnt vmcnt(1)
	ds_write_b16 v0, v48 offset:53248
	ds_write_b16_d16_hi v0, v48 offset:53392
	ds_write_b16 v0, v49 offset:53536
	ds_write_b16_d16_hi v0, v49 offset:53680
	v_lshlrev_b64 v[0:1], 11, v[64:65]
	v_lshl_add_u64 v[8:9], v[58:59], 0, v[0:1]
	v_lshl_add_u64 v[132:133], v[8:9], 0, v[134:135]
	global_load_dwordx3 v[12:14], v[62:63], off
	global_load_dwordx4 v[16:19], v[132:133], off offset:16
	global_load_dwordx4 v[20:23], v[132:133], off
	global_load_dwordx4 v[0:3], v[132:133], off offset:1040
	s_nop 0
	global_load_dwordx4 v[8:11], v[132:133], off offset:1024
	v_mad_i64_i32 v[32:33], s[26:27], v64, s37, v[60:61]
	global_load_dwordx2 v[48:49], v[32:33], off offset:2048
	v_sub_f32_e32 v15, v34, v75
	v_mul_f32_e32 v15, 0x3fb8aa3b, v15
	v_exp_f32_e32 v54, v15
	s_add_i32 s50, s50, 1
	v_lshl_add_u64 v[62:63], v[62:63], 0, s[22:23]
	v_add_u32_e32 v64, 64, v64
	s_cmp_lg_u32 s50, 31
	v_add_u32_e32 v66, 64, v66
	s_cbranch_scc0 .LBB0_665

.LBB0_687:
	s_or_b64 exec, exec, s[26:27]
	v_mov_b32_e32 v12, s49
	v_add_f32_e32 v14, s25, v12
	v_add_f32_e32 v12, s25, v75
	v_max_f32_e32 v14, v12, v14
	v_add_f32_e32 v13, s25, v13
	v_sub_f32_e32 v13, v13, v14
	v_mul_f32_e32 v13, 0x3fb8aa3b, v13
	v_exp_f32_e32 v13, v13
	s_nop 0
	ds_bpermute_b32 v142, v143, v13
	s_waitcnt vmcnt(4)
	ds_write_b128 v136, v[20:23]
	ds_write_b128 v136, v[16:19] offset:16
	s_waitcnt vmcnt(2)
	ds_write_b128 v136, v[8:11] offset:17408
	ds_write_b128 v136, v[0:3] offset:17424
	v_lshlrev_b32_e32 v16, 16, v8
	v_and_b32_e32 v8, 0xffff0000, v8
	s_waitcnt lgkmcnt(0)
	v_mul_f32_e32 v8, v142, v8
	v_cvt_pk_bf16_f32 v8, v8, s0
	ds_write_b16 v140, v8 offset:34960
	v_lshlrev_b32_e32 v8, 16, v9
	v_mul_f32_e32 v8, v142, v8
	v_cvt_pk_bf16_f32 v8, v8, s0
	ds_write_b16 v140, v8 offset:35104
	v_and_b32_e32 v8, 0xffff0000, v9
	v_mul_f32_e32 v8, v142, v8
	v_cvt_pk_bf16_f32 v8, v8, s0
	ds_write_b16 v140, v8 offset:35248
	v_lshlrev_b32_e32 v8, 16, v10
	v_mul_f32_e32 v8, v142, v8
	v_cvt_pk_bf16_f32 v8, v8, s0
	ds_write_b16 v140, v8 offset:35392
	v_and_b32_e32 v8, 0xffff0000, v10
	v_mul_f32_e32 v8, v142, v8
	v_cvt_pk_bf16_f32 v8, v8, s0
	ds_write_b16 v140, v8 offset:35536
	v_lshlrev_b32_e32 v8, 16, v11
	v_mul_f32_e32 v8, v142, v8
	v_cvt_pk_bf16_f32 v8, v8, s0
	ds_write_b16 v140, v8 offset:35680
	v_and_b32_e32 v8, 0xffff0000, v11
	v_mul_f32_e32 v8, v142, v8
	v_cvt_pk_bf16_f32 v8, v8, s0
	ds_write_b16 v140, v8 offset:35824
	v_lshlrev_b32_e32 v8, 16, v0
	v_and_b32_e32 v0, 0xffff0000, v0
	v_mul_f32_e32 v0, v142, v0
	v_cvt_pk_bf16_f32 v0, v0, s0
	ds_write_b16 v141, v0 offset:36112
	v_lshlrev_b32_e32 v0, 16, v1
	v_mul_f32_e32 v0, v142, v0
	v_cvt_pk_bf16_f32 v0, v0, s0
	ds_write_b16 v141, v0 offset:36256
	v_and_b32_e32 v0, 0xffff0000, v1
	v_mul_f32_e32 v0, v142, v0
	v_cvt_pk_bf16_f32 v0, v0, s0
	ds_write_b16 v141, v0 offset:36400
	v_lshlrev_b32_e32 v0, 16, v2
	v_mul_f32_e32 v0, v142, v0
	v_cvt_pk_bf16_f32 v0, v0, s0
	ds_write_b16 v141, v0 offset:36544
	v_and_b32_e32 v0, 0xffff0000, v2
	v_mul_f32_e32 v0, v142, v0
	v_cvt_pk_bf16_f32 v0, v0, s0
	ds_write_b16 v141, v0 offset:36688
	v_lshlrev_b32_e32 v0, 16, v3
	v_mul_f32_e32 v0, v142, v0
	v_cvt_pk_bf16_f32 v0, v0, s0
	ds_write_b16 v141, v0 offset:36832
	v_and_b32_e32 v0, 0xffff0000, v3
	v_mul_f32_e32 v16, v142, v16
	v_mul_f32_e32 v8, v142, v8
	v_mul_f32_e32 v0, v142, v0
	v_cvt_pk_bf16_f32 v16, v16, s0
	v_cvt_pk_bf16_f32 v8, v8, s0
	v_cvt_pk_bf16_f32 v0, v0, s0
	ds_write_b16 v140, v16 offset:34816
	ds_write_b16 v141, v8 offset:35968
	ds_write_b16 v141, v0 offset:36976
	s_waitcnt vmcnt(1)
	ds_write_b16 v77, v48 offset:60160
	ds_write_b16_d16_hi v77, v48 offset:60304
	ds_write_b16 v77, v49 offset:60448
	ds_write_b16_d16_hi v77, v49 offset:60592
	s_waitcnt lgkmcnt(0)
	s_barrier
	v_mov_b32_e32 v9, 0
	v_mov_b32_e32 v0, 0
	v_mov_b32_e32 v1, 0
	v_mov_b32_e32 v2, 0
	v_mov_b32_e32 v3, 0
	s_and_saveexec_b64 s[8:9], s[20:21]
	s_cbranch_execz .LBB0_689
	ds_read_b128 v[0:3], v44
	ds_read_b128 v[16:19], v44 offset:64
	ds_read_b128 v[20:23], v61 offset:17408
	ds_read_b128 v[48:51], v61 offset:17472
	s_waitcnt lgkmcnt(1)
	v_mfma_f32_16x16x32_bf16 v[0:3], v[0:3], v[20:23], 0
	ds_read_b128 v[20:23], v44 offset:128
	ds_read_b128 v[62:65], v44 offset:192
	s_waitcnt lgkmcnt(2)
	v_mfma_f32_16x16x32_bf16 v[0:3], v[16:19], v[48:51], v[0:3]
	ds_read_b128 v[16:19], v61 offset:17536
	ds_read_b128 v[48:51], v61 offset:17600
	s_waitcnt lgkmcnt(1)
	v_mfma_f32_16x16x32_bf16 v[0:3], v[20:23], v[16:19], v[0:3]
	s_waitcnt lgkmcnt(0)
	v_mfma_f32_16x16x32_bf16 v[0:3], v[62:65], v[48:51], v[0:3]
